# nt on the streaming A-operand (hidden activations) LDS-DMA loads of the P7 down-projection K-loop
# baseline (speedup 1.0000x reference)
; #define PG8_STAGE(bufoff, gbase, voff) do { _Pragma("unroll") for (int _i = 0; _i < 2; ++_i) \
;         __builtin_amdgcn_global_load_lds((const unsigned*)((const char*)(gbase) + (voff)[_i]), (LAS unsigned*)(lds + (bufoff) + ldsw + _i * 8192), 16, 0, 0); } while (0)
; #define PG8_LDA(dst, b, h) do { _Pragma("unroll") for (int m = 0; m < 4; ++m) _Pragma("unroll") for (int k = 0; k < 2; ++k) dst[m][k] = *(const LAS bf16x8*)(lds + PG8_SA(b, h) + aoff + m * 2048 + k * 1024); } while (0)
; #define PG8_LDB(dst, b, h) do { _Pragma("unroll") for (int n = 0; n < 2; ++n) _Pragma("unroll") for (int k = 0; k < 2; ++k) dst[n][k] = *(const LAS bf16x8*)(lds + PG8_SB(b, h) + boff + n * 2048 + k * 1024); } while (0)
; #define PG8_MMA(ai, bj, At, Bt) do { __builtin_amdgcn_s_setprio(1); _Pragma("unroll") for (int m = 0; m < 4; ++m) _Pragma("unroll") for (int n = 0; n < 2; ++n) _Pragma("unroll") for (int k = 0; k < 2; ++k) \
;         acc[ai][bj][m][n] = __builtin_amdgcn_mfma_f32_16x16x32_bf16(Bt[n][k], At[m][k], acc[ai][bj][m][n], 0, 0, 0); __builtin_amdgcn_s_setprio(0); } while (0)
; #define PG8_WAIT_V(n) asm volatile("s_waitcnt vmcnt(" #n ")" ::: "memory")
; #define PG8_WAIT_L(n) asm volatile("s_waitcnt lgkmcnt(" #n ")" ::: "memory")
; #define PG8_BAR __builtin_amdgcn_s_barrier()
; #define PG8_SCHED __builtin_amdgcn_sched_barrier(0)
; template <class Epi, class Sched>
; __device__ __forceinline__ void gemm_phase(LAS unsigned char* lds, const Gemm g, const Sched& S, const Epi& E) {
;     ...
;             const char* a1 = cA + (size_t)(t + 1) * kstep;
;             const char* a2 = last ? nA : cA + (size_t)(t + 2) * kstep; const char* b2 = last ? nB : cB + (size_t)(t + 2) * kstep;
;             const char* a3 = a2 + kstep; const char* b3 = b2 + kstep;
;             PG8_LDB(B0, 0, 0); PG8_LDB(B1, 0, 1); PG8_SCHED; PG8_LDA(At, 0, 0); PG8_STAGE(PG8_SA(1, 1), a1 + hstepA, voffA);
;             PG8_WAIT_V(8); PG8_WAIT_L(0); PG8_BAR; PG8_MMA(0, 0, At, B0); PG8_MMA(0, 1, At, B1); PG8_BAR; PG8_SCHED;
;             PG8_LDA(At, 0, 1); PG8_STAGE(PG8_SB(0, 0), b2, voffB); PG8_STAGE(PG8_SB(0, 1), b2 + hstepB, voffB); PG8_STAGE(PG8_SA(0, 0), a2, voffA);
;             PG8_WAIT_V(8); PG8_WAIT_L(0); PG8_BAR; PG8_MMA(1, 0, At, B0); PG8_MMA(1, 1, At, B1); PG8_BAR; PG8_SCHED;
.LBB0_1028:
	ds_read_b128 v[128:131], v191
	ds_read_b128 v[132:135], v191 offset:1024
	ds_read_b128 v[136:139], v191 offset:2048
	ds_read_b128 v[140:143], v191 offset:3072
	ds_read_b128 v[144:147], v192
	ds_read_b128 v[148:151], v192 offset:1024
	ds_read_b128 v[168:171], v192 offset:2048
	ds_read_b128 v[172:175], v192 offset:3072
	s_add_u32 s34, s30, 0x100
	s_addc_u32 s35, s31, 0
	s_cmpk_eq_i32 s55, 0x7c
	s_cselect_b32 s39, s23, s35
	s_cselect_b32 s38, s29, s34
	s_cselect_b32 s37, s21, s54
	s_cselect_b32 s36, s52, s53
	v_lshl_add_u64 v[188:189], s[30:31], 0, v[160:161]
	s_add_i32 m0, s33, 0xc000
	ds_read_b128 v[176:179], v193
	ds_read_b128 v[180:183], v193 offset:1024
	ds_read_b128 v[196:199], v193 offset:2048
	ds_read_b128 v[200:203], v193 offset:3072
	ds_read_b128 v[204:207], v193 offset:4096
	ds_read_b128 v[208:211], v193 offset:5120
	ds_read_b128 v[212:215], v193 offset:6144
	ds_read_b128 v[216:219], v193 offset:7168
	global_load_lds_dwordx4 v[188:189], off nt
	v_lshl_add_u64 v[188:189], s[30:31], 0, v[162:163]
	s_add_i32 m0, s33, 0xe000
	s_nop 0
	global_load_lds_dwordx4 v[188:189], off nt
	s_waitcnt vmcnt(8)
	s_waitcnt lgkmcnt(0)
	s_barrier
	s_setprio 1
	s_waitcnt lgkmcnt(0)
	v_mfma_f32_16x16x32_bf16 v[124:127], v[128:131], v[176:179], v[124:127]
	v_mfma_f32_16x16x32_bf16 v[120:123], v[136:139], v[176:179], v[120:123]
	v_mfma_f32_16x16x32_bf16 v[108:111], v[128:131], v[196:199], v[108:111]
	v_mfma_f32_16x16x32_bf16 v[104:107], v[136:139], v[196:199], v[104:107]
	v_mfma_f32_16x16x32_bf16 v[92:95], v[128:131], v[204:207], v[92:95]
	v_mfma_f32_16x16x32_bf16 v[88:91], v[136:139], v[204:207], v[88:91]
	v_mfma_f32_16x16x32_bf16 v[76:79], v[128:131], v[212:215], v[76:79]
	v_mfma_f32_16x16x32_bf16 v[72:75], v[136:139], v[212:215], v[72:75]
	v_mfma_f32_16x16x32_bf16 v[124:127], v[132:135], v[180:183], v[124:127]
	v_mfma_f32_16x16x32_bf16 v[120:123], v[140:143], v[180:183], v[120:123]
	v_mfma_f32_16x16x32_bf16 v[108:111], v[132:135], v[200:203], v[108:111]
	v_mfma_f32_16x16x32_bf16 v[104:107], v[140:143], v[200:203], v[104:107]
	v_mfma_f32_16x16x32_bf16 v[92:95], v[132:135], v[208:211], v[92:95]
	v_mfma_f32_16x16x32_bf16 v[88:91], v[140:143], v[208:211], v[88:91]
	v_mfma_f32_16x16x32_bf16 v[76:79], v[132:135], v[216:219], v[76:79]
	v_mfma_f32_16x16x32_bf16 v[72:75], v[140:143], v[216:219], v[72:75]
	s_setprio 0
	s_setprio 1
	v_mfma_f32_16x16x32_bf16 v[116:119], v[144:147], v[176:179], v[116:119]
	v_mfma_f32_16x16x32_bf16 v[112:115], v[168:171], v[176:179], v[112:115]
	v_mfma_f32_16x16x32_bf16 v[100:103], v[144:147], v[196:199], v[100:103]
	v_mfma_f32_16x16x32_bf16 v[96:99], v[168:171], v[196:199], v[96:99]
	v_mfma_f32_16x16x32_bf16 v[84:87], v[144:147], v[204:207], v[84:87]
	v_mfma_f32_16x16x32_bf16 v[80:83], v[168:171], v[204:207], v[80:83]
	v_mfma_f32_16x16x32_bf16 v[68:71], v[144:147], v[212:215], v[68:71]
	v_mfma_f32_16x16x32_bf16 v[64:67], v[168:171], v[212:215], v[64:67]
	v_mfma_f32_16x16x32_bf16 v[116:119], v[148:151], v[180:183], v[116:119]
	v_mfma_f32_16x16x32_bf16 v[112:115], v[172:175], v[180:183], v[112:115]
	v_mfma_f32_16x16x32_bf16 v[100:103], v[148:151], v[200:203], v[100:103]
	v_mfma_f32_16x16x32_bf16 v[96:99], v[172:175], v[200:203], v[96:99]
	v_mfma_f32_16x16x32_bf16 v[84:87], v[148:151], v[208:211], v[84:87]
	v_mfma_f32_16x16x32_bf16 v[80:83], v[172:175], v[208:211], v[80:83]
	v_mfma_f32_16x16x32_bf16 v[68:71], v[148:151], v[216:219], v[68:71]
	v_mfma_f32_16x16x32_bf16 v[64:67], v[172:175], v[216:219], v[64:67]
	s_setprio 0
	s_barrier
	s_add_i32 s30, s49, s3
	v_lshl_add_u64 v[188:189], s[36:37], 0, v[154:155]
	s_mov_b32 m0, s30
	ds_read_b128 v[176:179], v193 offset:16384
	ds_read_b128 v[180:183], v193 offset:17408
	ds_read_b128 v[196:199], v193 offset:18432
	ds_read_b128 v[200:203], v193 offset:19456
	ds_read_b128 v[204:207], v193 offset:20480
	ds_read_b128 v[208:211], v193 offset:21504
	ds_read_b128 v[212:215], v193 offset:22528
	ds_read_b128 v[216:219], v193 offset:23552
	global_load_lds_dwordx4 v[188:189], off
	s_add_i32 m0, s30, 0x2000
	s_add_u32 s30, s36, 0x200000
	v_lshl_add_u64 v[220:221], s[36:37], 0, v[158:159]
	s_addc_u32 s31, s37, 0
	s_add_i32 s56, s50, s3
	global_load_lds_dwordx4 v[220:221], off
	v_lshl_add_u64 v[222:223], s[30:31], 0, v[154:155]
	s_mov_b32 m0, s56
	v_lshl_add_u64 v[224:225], s[38:39], 0, v[156:157]
	global_load_lds_dwordx4 v[222:223], off
	v_lshl_add_u64 v[222:223], s[30:31], 0, v[158:159]
	s_add_i32 m0, s56, 0x2000
	s_nop 0
	global_load_lds_dwordx4 v[222:223], off
	v_lshl_add_u64 v[222:223], s[38:39], 0, v[152:153]
	s_mov_b32 m0, s33
	s_nop 0
	global_load_lds_dwordx4 v[222:223], off nt
	s_mov_b32 m0, s40
	s_nop 0
	global_load_lds_dwordx4 v[224:225], off nt
	s_waitcnt vmcnt(8)
	s_waitcnt lgkmcnt(0)
	s_barrier
; #define PG8_STAGE(bufoff, gbase, voff) do { _Pragma("unroll") for (int _i = 0; _i < 2; ++_i) \
;         __builtin_amdgcn_global_load_lds((const unsigned*)((const char*)(gbase) + (voff)[_i]), (LAS unsigned*)(lds + (bufoff) + ldsw + _i * 8192), 16, 0, 0); } while (0)
; #define PG8_LDA(dst, b, h) do { _Pragma("unroll") for (int m = 0; m < 4; ++m) _Pragma("unroll") for (int k = 0; k < 2; ++k) dst[m][k] = *(const LAS bf16x8*)(lds + PG8_SA(b, h) + aoff + m * 2048 + k * 1024); } while (0)
; #define PG8_LDB(dst, b, h) do { _Pragma("unroll") for (int n = 0; n < 2; ++n) _Pragma("unroll") for (int k = 0; k < 2; ++k) dst[n][k] = *(const LAS bf16x8*)(lds + PG8_SB(b, h) + boff + n * 2048 + k * 1024); } while (0)
; #define PG8_MMA(ai, bj, At, Bt) do { __builtin_amdgcn_s_setprio(1); _Pragma("unroll") for (int m = 0; m < 4; ++m) _Pragma("unroll") for (int n = 0; n < 2; ++n) _Pragma("unroll") for (int k = 0; k < 2; ++k) \
;         acc[ai][bj][m][n] = __builtin_amdgcn_mfma_f32_16x16x32_bf16(Bt[n][k], At[m][k], acc[ai][bj][m][n], 0, 0, 0); __builtin_amdgcn_s_setprio(0); } while (0)
; #define PG8_WAIT_V(n) asm volatile("s_waitcnt vmcnt(" #n ")" ::: "memory")
; #define PG8_WAIT_L(n) asm volatile("s_waitcnt lgkmcnt(" #n ")" ::: "memory")
; #define PG8_BAR __builtin_amdgcn_s_barrier()
; #define PG8_SCHED __builtin_amdgcn_sched_barrier(0)
; template <class Epi, class Sched>
; __device__ __forceinline__ void gemm_phase(LAS unsigned char* lds, const Gemm g, const Sched& S, const Epi& E) {
;     ...
;             PG8_WAIT_V(8); PG8_WAIT_L(0); PG8_BAR; PG8_MMA(1, 0, At, B0); PG8_MMA(1, 1, At, B1); PG8_BAR; PG8_SCHED;
;             PG8_LDB(B0, 1, 0); PG8_LDB(B1, 1, 1); PG8_SCHED; PG8_LDA(At, 1, 0); PG8_STAGE(PG8_SA(0, 1), a2 + hstepA, voffA);
;             PG8_WAIT_V(8); PG8_WAIT_L(0); PG8_BAR; PG8_MMA(0, 0, At, B0); PG8_MMA(0, 1, At, B1); PG8_BAR; PG8_SCHED;
	s_setprio 1
	s_waitcnt lgkmcnt(0)
	v_mfma_f32_16x16x32_bf16 v[60:63], v[128:131], v[176:179], v[60:63]
	v_mfma_f32_16x16x32_bf16 v[56:59], v[136:139], v[176:179], v[56:59]
	v_mfma_f32_16x16x32_bf16 v[44:47], v[128:131], v[196:199], v[44:47]
	v_mfma_f32_16x16x32_bf16 v[40:43], v[136:139], v[196:199], v[40:43]
	v_mfma_f32_16x16x32_bf16 v[28:31], v[128:131], v[204:207], v[28:31]
	v_mfma_f32_16x16x32_bf16 v[24:27], v[136:139], v[204:207], v[24:27]
	v_mfma_f32_16x16x32_bf16 v[12:15], v[128:131], v[212:215], v[12:15]
	v_mfma_f32_16x16x32_bf16 v[8:11], v[136:139], v[212:215], v[8:11]
	v_mfma_f32_16x16x32_bf16 v[60:63], v[132:135], v[180:183], v[60:63]
	v_mfma_f32_16x16x32_bf16 v[56:59], v[140:143], v[180:183], v[56:59]
	v_mfma_f32_16x16x32_bf16 v[44:47], v[132:135], v[200:203], v[44:47]
	v_mfma_f32_16x16x32_bf16 v[40:43], v[140:143], v[200:203], v[40:43]
	v_mfma_f32_16x16x32_bf16 v[28:31], v[132:135], v[208:211], v[28:31]
	v_mfma_f32_16x16x32_bf16 v[24:27], v[140:143], v[208:211], v[24:27]
	v_mfma_f32_16x16x32_bf16 v[12:15], v[132:135], v[216:219], v[12:15]
	v_mfma_f32_16x16x32_bf16 v[8:11], v[140:143], v[216:219], v[8:11]
	s_setprio 0
	s_setprio 1
	v_mfma_f32_16x16x32_bf16 v[52:55], v[144:147], v[176:179], v[52:55]
	v_mfma_f32_16x16x32_bf16 v[48:51], v[168:171], v[176:179], v[48:51]
	v_mfma_f32_16x16x32_bf16 v[36:39], v[144:147], v[196:199], v[36:39]
	v_mfma_f32_16x16x32_bf16 v[32:35], v[168:171], v[196:199], v[32:35]
	v_mfma_f32_16x16x32_bf16 v[20:23], v[144:147], v[204:207], v[20:23]
	v_mfma_f32_16x16x32_bf16 v[16:19], v[168:171], v[204:207], v[16:19]
	v_mfma_f32_16x16x32_bf16 v[4:7], v[144:147], v[212:215], v[4:7]
	v_mfma_f32_16x16x32_bf16 v[0:3], v[168:171], v[212:215], v[0:3]
	v_mfma_f32_16x16x32_bf16 v[52:55], v[148:151], v[180:183], v[52:55]
	v_mfma_f32_16x16x32_bf16 v[48:51], v[172:175], v[180:183], v[48:51]
	v_mfma_f32_16x16x32_bf16 v[36:39], v[148:151], v[200:203], v[36:39]
	v_mfma_f32_16x16x32_bf16 v[32:35], v[172:175], v[200:203], v[32:35]
	v_mfma_f32_16x16x32_bf16 v[20:23], v[148:151], v[208:211], v[20:23]
	v_mfma_f32_16x16x32_bf16 v[16:19], v[172:175], v[208:211], v[16:19]
	v_mfma_f32_16x16x32_bf16 v[4:7], v[148:151], v[216:219], v[4:7]
	v_mfma_f32_16x16x32_bf16 v[0:3], v[172:175], v[216:219], v[0:3]
	s_setprio 0
	s_barrier
	s_add_i32 s56, 0, 0x18000
	s_add_i32 s57, 0, 0x1c000
	v_add_u32_e32 v140, s56, v187
	v_add_u32_e32 v172, s57, v187
	ds_read_b128 v[128:131], v140
	ds_read_b128 v[132:135], v140 offset:1024
	ds_read_b128 v[136:139], v140 offset:2048
	ds_read_b128 v[140:143], v140 offset:3072
	ds_read_b128 v[144:147], v172
	ds_read_b128 v[148:151], v172 offset:1024
	ds_read_b128 v[168:171], v172 offset:2048
	ds_read_b128 v[172:175], v172 offset:3072
	s_add_u32 s30, s38, 0x200000
	s_addc_u32 s31, s39, 0
	s_mov_b32 m0, s41
	v_lshl_add_u64 v[226:227], s[30:31], 0, v[152:153]
	ds_read_b128 v[176:179], v193 offset:32768
	ds_read_b128 v[180:183], v193 offset:33792
	ds_read_b128 v[196:199], v193 offset:34816
	ds_read_b128 v[200:203], v193 offset:35840
	ds_read_b128 v[204:207], v193 offset:36864
	ds_read_b128 v[208:211], v193 offset:37888
	ds_read_b128 v[212:215], v193 offset:38912
	ds_read_b128 v[216:219], v193 offset:39936
	global_load_lds_dwordx4 v[226:227], off nt
	v_lshl_add_u64 v[226:227], s[30:31], 0, v[156:157]
	s_mov_b32 m0, s42
	s_nop 0
	global_load_lds_dwordx4 v[226:227], off nt
	s_waitcnt vmcnt(8)
	s_waitcnt lgkmcnt(0)
	s_barrier
	s_setprio 1
	s_waitcnt lgkmcnt(0)
	v_mfma_f32_16x16x32_bf16 v[124:127], v[128:131], v[176:179], v[124:127]
	v_mfma_f32_16x16x32_bf16 v[120:123], v[136:139], v[176:179], v[120:123]
	v_mfma_f32_16x16x32_bf16 v[108:111], v[128:131], v[196:199], v[108:111]
	v_mfma_f32_16x16x32_bf16 v[104:107], v[136:139], v[196:199], v[104:107]
	v_mfma_f32_16x16x32_bf16 v[92:95], v[128:131], v[204:207], v[92:95]
	v_mfma_f32_16x16x32_bf16 v[88:91], v[136:139], v[204:207], v[88:91]
	v_mfma_f32_16x16x32_bf16 v[76:79], v[128:131], v[212:215], v[76:79]
	v_mfma_f32_16x16x32_bf16 v[72:75], v[136:139], v[212:215], v[72:75]
	v_mfma_f32_16x16x32_bf16 v[124:127], v[132:135], v[180:183], v[124:127]
	v_mfma_f32_16x16x32_bf16 v[120:123], v[140:143], v[180:183], v[120:123]
	v_mfma_f32_16x16x32_bf16 v[108:111], v[132:135], v[200:203], v[108:111]
	v_mfma_f32_16x16x32_bf16 v[104:107], v[140:143], v[200:203], v[104:107]
	v_mfma_f32_16x16x32_bf16 v[92:95], v[132:135], v[208:211], v[92:95]
	v_mfma_f32_16x16x32_bf16 v[88:91], v[140:143], v[208:211], v[88:91]
	v_mfma_f32_16x16x32_bf16 v[76:79], v[132:135], v[216:219], v[76:79]
	v_mfma_f32_16x16x32_bf16 v[72:75], v[140:143], v[216:219], v[72:75]
	s_setprio 0
	s_setprio 1
	v_mfma_f32_16x16x32_bf16 v[116:119], v[144:147], v[176:179], v[116:119]
	v_mfma_f32_16x16x32_bf16 v[112:115], v[168:171], v[176:179], v[112:115]
	v_mfma_f32_16x16x32_bf16 v[100:103], v[144:147], v[196:199], v[100:103]
	v_mfma_f32_16x16x32_bf16 v[96:99], v[168:171], v[196:199], v[96:99]
	v_mfma_f32_16x16x32_bf16 v[84:87], v[144:147], v[204:207], v[84:87]
	v_mfma_f32_16x16x32_bf16 v[80:83], v[168:171], v[204:207], v[80:83]
	v_mfma_f32_16x16x32_bf16 v[68:71], v[144:147], v[212:215], v[68:71]
	v_mfma_f32_16x16x32_bf16 v[64:67], v[168:171], v[212:215], v[64:67]
	v_mfma_f32_16x16x32_bf16 v[116:119], v[148:151], v[180:183], v[116:119]
	v_mfma_f32_16x16x32_bf16 v[112:115], v[172:175], v[180:183], v[112:115]
	v_mfma_f32_16x16x32_bf16 v[100:103], v[148:151], v[200:203], v[100:103]
	v_mfma_f32_16x16x32_bf16 v[96:99], v[172:175], v[200:203], v[96:99]
	v_mfma_f32_16x16x32_bf16 v[84:87], v[148:151], v[208:211], v[84:87]
	v_mfma_f32_16x16x32_bf16 v[80:83], v[172:175], v[208:211], v[80:83]
	v_mfma_f32_16x16x32_bf16 v[68:71], v[148:151], v[216:219], v[68:71]
	v_mfma_f32_16x16x32_bf16 v[64:67], v[172:175], v[216:219], v[64:67]
	s_setprio 0
	s_barrier
; #define PG8_STAGE(bufoff, gbase, voff) do { _Pragma("unroll") for (int _i = 0; _i < 2; ++_i) \
;         __builtin_amdgcn_global_load_lds((const unsigned*)((const char*)(gbase) + (voff)[_i]), (LAS unsigned*)(lds + (bufoff) + ldsw + _i * 8192), 16, 0, 0); } while (0)
; #define PG8_LDA(dst, b, h) do { _Pragma("unroll") for (int m = 0; m < 4; ++m) _Pragma("unroll") for (int k = 0; k < 2; ++k) dst[m][k] = *(const LAS bf16x8*)(lds + PG8_SA(b, h) + aoff + m * 2048 + k * 1024); } while (0)
; #define PG8_MMA(ai, bj, At, Bt) do { __builtin_amdgcn_s_setprio(1); _Pragma("unroll") for (int m = 0; m < 4; ++m) _Pragma("unroll") for (int n = 0; n < 2; ++n) _Pragma("unroll") for (int k = 0; k < 2; ++k) \
;         acc[ai][bj][m][n] = __builtin_amdgcn_mfma_f32_16x16x32_bf16(Bt[n][k], At[m][k], acc[ai][bj][m][n], 0, 0, 0); __builtin_amdgcn_s_setprio(0); } while (0)
; #define PG8_WAIT_V(n) asm volatile("s_waitcnt vmcnt(" #n ")" ::: "memory")
; #define PG8_WAIT_L(n) asm volatile("s_waitcnt lgkmcnt(" #n ")" ::: "memory")
; #define PG8_BAR __builtin_amdgcn_s_barrier()
; #define PG8_SCHED __builtin_amdgcn_sched_barrier(0)
; template <class Epi, class Sched>
; __device__ __forceinline__ void gemm_phase(LAS unsigned char* lds, const Gemm g, const Sched& S, const Epi& E) {
;     ...
;             PG8_LDA(At, 1, 1); PG8_STAGE(PG8_SB(1, 0), b3, voffB); PG8_STAGE(PG8_SB(1, 1), b3 + hstepB, voffB); PG8_STAGE(PG8_SA(1, 0), a3, voffA);
;             PG8_WAIT_V(8); PG8_WAIT_L(0); PG8_BAR; PG8_MMA(1, 0, At, B0); PG8_MMA(1, 1, At, B1); PG8_BAR; PG8_SCHED;
;         }
;         if (wr == 0) PG8_BAR;
	s_add_i32 s30, s56, s3
	v_lshl_add_u64 v[188:189], v[188:189], 0, s[16:17]
	s_mov_b32 m0, s30
	ds_read_b128 v[176:179], v193 offset:49152
	ds_read_b128 v[180:183], v193 offset:50176
	ds_read_b128 v[196:199], v193 offset:51200
	ds_read_b128 v[200:203], v193 offset:52224
	ds_read_b128 v[204:207], v193 offset:53248
	ds_read_b128 v[208:211], v193 offset:54272
	ds_read_b128 v[212:215], v193 offset:55296
	ds_read_b128 v[216:219], v193 offset:56320
	global_load_lds_dwordx4 v[188:189], off
	s_add_i32 m0, s30, 0x2000
	s_add_u32 s30, s36, 0x200080
	v_lshl_add_u64 v[188:189], v[220:221], 0, s[16:17]
	s_addc_u32 s31, s37, 0
	s_add_i32 s36, s57, s3
	global_load_lds_dwordx4 v[188:189], off
	v_lshl_add_u64 v[188:189], s[30:31], 0, v[154:155]
	s_mov_b32 m0, s36
	s_nop 0
	global_load_lds_dwordx4 v[188:189], off
	v_lshl_add_u64 v[188:189], s[30:31], 0, v[158:159]
	s_add_i32 m0, s36, 0x2000
	s_nop 0
	global_load_lds_dwordx4 v[188:189], off
	v_lshl_add_u64 v[188:189], v[222:223], 0, s[16:17]
	s_mov_b32 m0, s44
	s_nop 0
	global_load_lds_dwordx4 v[188:189], off nt
	v_lshl_add_u64 v[188:189], v[224:225], 0, s[16:17]
	s_mov_b32 m0, s45
	s_nop 0
	global_load_lds_dwordx4 v[188:189], off nt
	s_waitcnt vmcnt(8)
	s_waitcnt lgkmcnt(0)
	s_barrier
	s_setprio 1
	s_waitcnt lgkmcnt(0)
	v_mfma_f32_16x16x32_bf16 v[60:63], v[128:131], v[176:179], v[60:63]
	v_mfma_f32_16x16x32_bf16 v[56:59], v[136:139], v[176:179], v[56:59]
	v_mfma_f32_16x16x32_bf16 v[44:47], v[128:131], v[196:199], v[44:47]
	v_mfma_f32_16x16x32_bf16 v[40:43], v[136:139], v[196:199], v[40:43]
	v_mfma_f32_16x16x32_bf16 v[28:31], v[128:131], v[204:207], v[28:31]
	v_mfma_f32_16x16x32_bf16 v[24:27], v[136:139], v[204:207], v[24:27]
	v_mfma_f32_16x16x32_bf16 v[12:15], v[128:131], v[212:215], v[12:15]
	v_mfma_f32_16x16x32_bf16 v[8:11], v[136:139], v[212:215], v[8:11]
	v_mfma_f32_16x16x32_bf16 v[60:63], v[132:135], v[180:183], v[60:63]
	v_mfma_f32_16x16x32_bf16 v[56:59], v[140:143], v[180:183], v[56:59]
	v_mfma_f32_16x16x32_bf16 v[44:47], v[132:135], v[200:203], v[44:47]
	v_mfma_f32_16x16x32_bf16 v[40:43], v[140:143], v[200:203], v[40:43]
	v_mfma_f32_16x16x32_bf16 v[28:31], v[132:135], v[208:211], v[28:31]
	v_mfma_f32_16x16x32_bf16 v[24:27], v[140:143], v[208:211], v[24:27]
	v_mfma_f32_16x16x32_bf16 v[12:15], v[132:135], v[216:219], v[12:15]
	v_mfma_f32_16x16x32_bf16 v[8:11], v[140:143], v[216:219], v[8:11]
	s_setprio 0
	s_setprio 1
	v_mfma_f32_16x16x32_bf16 v[52:55], v[144:147], v[176:179], v[52:55]
	v_mfma_f32_16x16x32_bf16 v[48:51], v[168:171], v[176:179], v[48:51]
	v_mfma_f32_16x16x32_bf16 v[36:39], v[144:147], v[196:199], v[36:39]
	v_mfma_f32_16x16x32_bf16 v[32:35], v[168:171], v[196:199], v[32:35]
	v_mfma_f32_16x16x32_bf16 v[20:23], v[144:147], v[204:207], v[20:23]
	v_mfma_f32_16x16x32_bf16 v[16:19], v[168:171], v[204:207], v[16:19]
	v_mfma_f32_16x16x32_bf16 v[4:7], v[144:147], v[212:215], v[4:7]
	v_mfma_f32_16x16x32_bf16 v[0:3], v[168:171], v[212:215], v[0:3]
	v_mfma_f32_16x16x32_bf16 v[52:55], v[148:151], v[180:183], v[52:55]
	v_mfma_f32_16x16x32_bf16 v[48:51], v[172:175], v[180:183], v[48:51]
	v_mfma_f32_16x16x32_bf16 v[36:39], v[148:151], v[200:203], v[36:39]
	v_mfma_f32_16x16x32_bf16 v[32:35], v[172:175], v[200:203], v[32:35]
	v_mfma_f32_16x16x32_bf16 v[20:23], v[148:151], v[208:211], v[20:23]
	v_mfma_f32_16x16x32_bf16 v[16:19], v[172:175], v[208:211], v[16:19]
	v_mfma_f32_16x16x32_bf16 v[4:7], v[148:151], v[216:219], v[4:7]
	v_mfma_f32_16x16x32_bf16 v[0:3], v[172:175], v[216:219], v[0:3]
	s_setprio 0
	s_barrier
	s_add_i32 s55, s55, 2
	s_add_u32 s53, s53, 0x100
	s_addc_u32 s54, s54, 0
	s_cmpk_gt_u32 s55, 0x7d
	s_mov_b64 s[30:31], s[34:35]
	s_cbranch_scc0 .LBB0_1028
	s_and_b64 vcc, exec, s[18:19]
	s_cbranch_vccz .LBB0_1031
	s_barrier
